# v23 + removed the store-ack drain (vmcnt(0)) between the main GEMM epilogue and the small-tile tail path in P2/P8/P9/P10/P11
# baseline (speedup 1.0000x reference)
.LBB0_1025:
	s_or_b64 exec, exec, s[8:9]
	s_and_b64 vcc, exec, s[6:7]
	s_mov_b64 s[6:7], -1
	s_cbranch_vccnz .LBB0_906
	s_andn2_b64 vcc, exec, s[16:17]
	s_cbranch_vccnz .LBB0_905
	s_barrier
	s_branch .LBB0_905
.LBB0_1028:
	s_barrier
.LBB0_1029:
	s_and_b64 vcc, exec, s[0:1]
	v_readfirstlane_b32 s0, v1
	s_cbranch_vccnz .LBB0_1085
	s_cmpk_lt_u32 s0, 0x100
	s_cselect_b64 s[14:15], -1, 0
	v_lshlrev_b32_e32 v2, 3, v1
	s_lshr_b32 s3, s0, 2
	v_and_b32_e32 v61, 0x78, v2
	v_and_or_b32 v2, s3, 48, v169
	v_mul_u32_u24_e32 v62, 0x110, v2
	s_bfe_u32 s3, s0, 0x20006
	v_lshlrev_b32_e32 v2, 2, v171
	v_lshl_or_b32 v63, s3, 4, v2
	s_lshl_b32 s3, s3, 2
	s_add_i32 s3, s3, 0
	s_add_i32 s16, s3, 0x13200
	s_movk_i32 s3, 0x50
	s_lshr_b32 s1, s0, 6
	v_lshlrev_b32_e32 v38, 1, v61
	v_mov_b32_e32 v39, 0
	v_cmp_gt_u32_e64 s[4:5], s3, v1
	v_add_u32_e32 v2, 0x200, v1
	s_movk_i32 s3, 0x300
	v_lshl_add_u64 v[42:43], s[10:11], 0, v[38:39]
	s_lshl_b32 s11, s1, 2
	v_lshrrev_b32_e32 v64, 4, v2
	v_cmp_gt_u32_e64 s[6:7], s3, v1
	v_or_b32_e32 v2, 0x400, v1
	s_movk_i32 s3, 0x500
	v_cmp_gt_u32_e64 s[8:9], s3, v2
	s_and_b32 s3, s11, 0xffffff0
	s_add_i32 s11, s11, 32
	s_waitcnt lgkmcnt(0)
	v_lshrrev_b32_e32 v3, 4, v2
	s_and_b32 s22, s11, 0x1ffffff0
	s_movk_i32 s10, 0x110
	v_cndmask_b32_e64 v66, 0, v3, s[8:9]
	v_mul_u32_u24_e32 v69, 0x110, v3
	v_or_b32_e32 v3, s22, v169
	v_or_b32_e32 v2, s3, v169
	v_mul_lo_u32 v71, v3, s10
	v_lshlrev_b32_e32 v7, 4, v3
	v_lshlrev_b32_e32 v3, 12, v1
	v_lshl_add_u64 v[40:41], s[64:65], 0, v[38:39]
	v_mul_lo_u32 v70, v2, s10
	v_lshlrev_b32_e32 v6, 4, v2
	v_lshlrev_b32_e32 v2, 4, v169
	v_and_b32_e32 v38, 0xf000, v3
	v_readlane_b32 s68, v238, 5
	v_mov_b32_e32 v3, v39
	v_readlane_b32 s76, v238, 13
	v_readlane_b32 s77, v238, 14
	v_lshl_add_u64 v[4:5], s[28:29], 0, v[2:3]
	s_mov_b64 s[10:11], 0x5c00100
	v_lshrrev_b32_e32 v60, 4, v1
	s_add_u32 s23, s28, 0xea61400
	v_readlane_b32 s78, v238, 15
	v_readlane_b32 s79, v238, 16
	v_readlane_b32 s76, v238, 53
	v_lshl_add_u64 v[46:47], v[4:5], 0, s[10:11]
	s_mov_b64 s[10:11], 0xb00100
	v_add_u32_e32 v75, s16, v2
	v_mbcnt_lo_u32_b32 v2, -1, 0
	v_cmp_eq_u32_e64 s[0:1], 0, v171
	v_cndmask_b32_e64 v65, 0, v64, s[6:7]
	v_mul_u32_u24_e32 v67, 0x110, v60
	v_mul_u32_u24_e32 v68, 0x110, v64
	v_mul_u32_u24_e32 v72, 0x110, v169
	s_addc_u32 s33, s29, 0
	v_readlane_b32 s77, v238, 54
	v_lshl_add_u64 v[44:45], s[78:79], 0, v[38:39]
	v_lshl_add_u64 v[48:49], v[4:5], 0, s[10:11]
	s_movk_i32 s35, 0x1600
	s_movk_i32 s52, 0xb00
	s_movk_i32 s53, 0x3fff
	s_movk_i32 s54, 0x4400
	v_add_u32_e32 v73, s16, v6
	v_add_u32_e32 v74, s16, v7
	v_mbcnt_hi_u32_b32 v76, -1, v2
	s_mov_b32 s55, s2
	v_readlane_b32 s69, v238, 6
	v_readlane_b32 s70, v238, 7
	v_readlane_b32 s71, v238, 8
	v_readlane_b32 s72, v238, 9
	v_readlane_b32 s73, v238, 10
	v_readlane_b32 s74, v238, 11
	v_readlane_b32 s75, v238, 12
	v_readlane_b32 s80, v238, 17
	v_readlane_b32 s81, v238, 18
	v_readlane_b32 s82, v238, 19
	v_readlane_b32 s83, v238, 20
	s_branch .LBB0_1032

.LBB0_2873:
	v_lshl_add_u32 v158, s40, 8, v169
	v_lshl_or_b32 v130, s56, 8, v171
	v_ashrrev_i32_e32 v159, 31, v158
	v_ashrrev_i32_e32 v131, 31, v130
	v_lshlrev_b64 v[132:133], 11, v[158:159]
	v_lshlrev_b64 v[160:161], 1, v[130:131]
	v_or_b32_e32 v130, 16, v158
	v_lshl_add_u64 v[132:133], s[62:63], 0, v[132:133]
	v_ashrrev_i32_e32 v131, 31, v130
	v_lshl_add_u64 v[164:165], v[132:133], 0, v[160:161]
	v_lshlrev_b64 v[130:131], 11, v[130:131]
	global_load_dwordx4 v[134:137], v[164:165], off
	global_load_dwordx4 v[176:179], v[164:165], off offset:256
	v_lshl_add_u64 v[130:131], s[62:63], 0, v[130:131]
	v_lshl_add_u64 v[196:197], v[130:131], 0, v[160:161]
	global_load_dwordx4 v[180:183], v[196:197], off
	global_load_dwordx4 v[184:187], v[196:197], off offset:256
	v_or_b32_e32 v130, 32, v158
	v_ashrrev_i32_e32 v131, 31, v130
	v_lshlrev_b64 v[130:131], 11, v[130:131]
	v_lshl_add_u64 v[130:131], s[62:63], 0, v[130:131]
	v_lshl_add_u64 v[166:167], v[130:131], 0, v[160:161]
	global_load_dwordx4 v[188:191], v[166:167], off
	v_or_b32_e32 v130, 48, v158
	v_ashrrev_i32_e32 v131, 31, v130
	v_lshlrev_b64 v[130:131], 11, v[130:131]
	v_lshl_add_u64 v[130:131], s[62:63], 0, v[130:131]
	v_lshl_add_u64 v[162:163], v[130:131], 0, v[160:161]
	global_load_dwordx4 v[192:195], v[166:167], off offset:256
	global_load_dwordx4 v[138:141], v[162:163], off
	global_load_dwordx4 v[130:133], v[162:163], off offset:256
	s_andn2_b64 vcc, exec, s[0:1]
	s_mov_b64 s[0:1], -1
	s_waitcnt vmcnt(0)
	v_lshlrev_b32_e32 v200, 16, v136
	v_and_b32_e32 v201, 0xffff0000, v136
	v_lshlrev_b32_e32 v136, 16, v137
	v_and_b32_e32 v137, 0xffff0000, v137
	v_lshlrev_b32_e32 v202, 16, v176
	v_and_b32_e32 v203, 0xffff0000, v176
	v_lshlrev_b32_e32 v176, 16, v177
	v_and_b32_e32 v177, 0xffff0000, v177
	v_lshlrev_b32_e32 v204, 16, v178
	v_and_b32_e32 v205, 0xffff0000, v178
	v_lshlrev_b32_e32 v178, 16, v179
	v_and_b32_e32 v179, 0xffff0000, v179
	v_lshlrev_b32_e32 v198, 16, v134
	v_and_b32_e32 v199, 0xffff0000, v134
	v_lshlrev_b32_e32 v134, 16, v135
	v_and_b32_e32 v135, 0xffff0000, v135
	v_pk_mul_f32 v[124:125], v[124:125], v[136:137]
	v_pk_mul_f32 v[120:121], v[120:121], v[176:177]
	v_pk_mul_f32 v[136:137], v[112:113], v[178:179]
	v_lshlrev_b32_e32 v176, 16, v180
	v_and_b32_e32 v177, 0xffff0000, v180
	v_lshlrev_b32_e32 v178, 16, v181
	v_and_b32_e32 v179, 0xffff0000, v181
	v_lshlrev_b32_e32 v180, 16, v182
	v_and_b32_e32 v181, 0xffff0000, v182
	v_lshlrev_b32_e32 v182, 16, v183
	v_and_b32_e32 v183, 0xffff0000, v183
	v_pk_mul_f32 v[126:127], v[126:127], v[198:199]
	v_pk_mul_f32 v[128:129], v[128:129], v[134:135]
	v_pk_mul_f32 v[122:123], v[122:123], v[200:201]
	v_lshlrev_b32_e32 v198, 16, v184
	v_and_b32_e32 v199, 0xffff0000, v184
	v_lshlrev_b32_e32 v184, 16, v185
	v_and_b32_e32 v185, 0xffff0000, v185
	v_pk_mul_f32 v[114:115], v[114:115], v[176:177]
	v_pk_mul_f32 v[116:117], v[116:117], v[178:179]
	v_pk_mul_f32 v[106:107], v[106:107], v[180:181]
	v_pk_mul_f32 v[108:109], v[108:109], v[182:183]
	v_pk_mul_f32 v[118:119], v[118:119], v[202:203]
	v_pk_mul_f32 v[134:135], v[110:111], v[204:205]
	v_lshlrev_b32_e32 v200, 16, v186
	v_and_b32_e32 v201, 0xffff0000, v186
	v_cvt_pk_bf16_f32 v110, v126, v127
	v_cvt_pk_bf16_f32 v111, v128, v129
	v_cvt_pk_bf16_f32 v112, v122, v123
	v_cvt_pk_bf16_f32 v113, v124, v125
	v_pk_mul_f32 v[122:123], v[102:103], v[198:199]
	v_pk_mul_f32 v[124:125], v[104:105], v[184:185]
	v_cvt_pk_bf16_f32 v102, v114, v115
	v_cvt_pk_bf16_f32 v103, v116, v117
	v_cvt_pk_bf16_f32 v104, v106, v107
	v_cvt_pk_bf16_f32 v105, v108, v109
	v_cvt_pk_bf16_f32 v118, v118, v119
	v_cvt_pk_bf16_f32 v119, v120, v121
	v_cvt_pk_bf16_f32 v120, v134, v135
	v_cvt_pk_bf16_f32 v121, v136, v137
	global_store_dwordx4 v[164:165], v[110:113], off
	global_store_dwordx4 v[164:165], v[118:121], off offset:256
	global_store_dwordx4 v[196:197], v[102:105], off
	s_nop 1
	v_pk_mul_f32 v[102:103], v[98:99], v[200:201]
	v_lshlrev_b32_e32 v98, 16, v187
	v_and_b32_e32 v99, 0xffff0000, v187
	v_pk_mul_f32 v[104:105], v[100:101], v[98:99]
	v_cvt_pk_bf16_f32 v98, v122, v123
	v_cvt_pk_bf16_f32 v99, v124, v125
	v_cvt_pk_bf16_f32 v100, v102, v103
	v_cvt_pk_bf16_f32 v101, v104, v105
	global_store_dwordx4 v[196:197], v[98:101], off offset:256
	v_lshlrev_b32_e32 v104, 16, v189
	v_and_b32_e32 v105, 0xffff0000, v189
	v_lshlrev_b32_e32 v98, 16, v188
	v_and_b32_e32 v99, 0xffff0000, v188
	v_pk_mul_f32 v[102:103], v[94:95], v[98:99]
	v_add_u32_e32 v94, 0x80, v158
	v_ashrrev_i32_e32 v95, 31, v94
	v_lshlrev_b64 v[94:95], 11, v[94:95]
	v_lshl_add_u64 v[94:95], s[62:63], 0, v[94:95]
	v_lshl_add_u64 v[94:95], v[94:95], 0, v[160:161]
	global_load_dwordx4 v[98:101], v[94:95], off
	v_pk_mul_f32 v[96:97], v[96:97], v[104:105]
	v_lshlrev_b32_e32 v104, 16, v190
	v_and_b32_e32 v105, 0xffff0000, v190
	v_pk_mul_f32 v[104:105], v[90:91], v[104:105]
	v_lshlrev_b32_e32 v90, 16, v191
	v_and_b32_e32 v91, 0xffff0000, v191
	v_pk_mul_f32 v[106:107], v[92:93], v[90:91]
	v_cvt_pk_bf16_f32 v90, v102, v103
	v_cvt_pk_bf16_f32 v91, v96, v97
	v_cvt_pk_bf16_f32 v92, v104, v105
	v_cvt_pk_bf16_f32 v93, v106, v107
	v_lshlrev_b32_e32 v96, 16, v193
	v_and_b32_e32 v97, 0xffff0000, v193
	global_store_dwordx4 v[166:167], v[90:93], off
	v_pk_mul_f32 v[88:89], v[88:89], v[96:97]
	v_lshlrev_b32_e32 v96, 16, v194
	v_lshlrev_b32_e32 v90, 16, v192
	v_and_b32_e32 v91, 0xffff0000, v192
	v_and_b32_e32 v97, 0xffff0000, v194
	v_pk_mul_f32 v[86:87], v[86:87], v[90:91]
	global_load_dwordx4 v[90:93], v[94:95], off offset:256
	v_pk_mul_f32 v[96:97], v[82:83], v[96:97]
	v_lshlrev_b32_e32 v82, 16, v195
	v_and_b32_e32 v83, 0xffff0000, v195
	v_pk_mul_f32 v[102:103], v[84:85], v[82:83]
	v_cvt_pk_bf16_f32 v82, v86, v87
	v_cvt_pk_bf16_f32 v83, v88, v89
	v_cvt_pk_bf16_f32 v84, v96, v97
	v_cvt_pk_bf16_f32 v85, v102, v103
	global_store_dwordx4 v[166:167], v[82:85], off offset:256
	v_lshlrev_b32_e32 v88, 16, v139
	v_and_b32_e32 v89, 0xffff0000, v139
	v_lshlrev_b32_e32 v82, 16, v138
	v_and_b32_e32 v83, 0xffff0000, v138
	v_pk_mul_f32 v[86:87], v[78:79], v[82:83]
	v_add_u32_e32 v78, 0x90, v158
	v_ashrrev_i32_e32 v79, 31, v78
	v_lshlrev_b64 v[78:79], 11, v[78:79]
	v_lshl_add_u64 v[78:79], s[62:63], 0, v[78:79]
	v_lshl_add_u64 v[78:79], v[78:79], 0, v[160:161]
	global_load_dwordx4 v[82:85], v[78:79], off
	v_pk_mul_f32 v[80:81], v[80:81], v[88:89]
	v_lshlrev_b32_e32 v88, 16, v140
	v_and_b32_e32 v89, 0xffff0000, v140
	v_pk_mul_f32 v[88:89], v[74:75], v[88:89]
	v_lshlrev_b32_e32 v74, 16, v141
	v_and_b32_e32 v75, 0xffff0000, v141
	v_pk_mul_f32 v[96:97], v[76:77], v[74:75]
	v_cvt_pk_bf16_f32 v75, v80, v81
	v_lshlrev_b32_e32 v80, 16, v131
	v_and_b32_e32 v81, 0xffff0000, v131
	v_pk_mul_f32 v[72:73], v[72:73], v[80:81]
	v_lshlrev_b32_e32 v80, 16, v132
	v_and_b32_e32 v81, 0xffff0000, v132
	v_pk_mul_f32 v[80:81], v[66:67], v[80:81]
	v_lshlrev_b32_e32 v66, 16, v133
	v_and_b32_e32 v67, 0xffff0000, v133
	v_cvt_pk_bf16_f32 v74, v86, v87
	v_pk_mul_f32 v[86:87], v[68:69], v[66:67]
	v_add_u32_e32 v68, 0xa0, v158
	v_cvt_pk_bf16_f32 v76, v88, v89
	v_cvt_pk_bf16_f32 v77, v96, v97
	v_ashrrev_i32_e32 v69, 31, v68
	global_store_dwordx4 v[162:163], v[74:77], off
	v_lshlrev_b64 v[68:69], 11, v[68:69]
	v_lshl_add_u64 v[68:69], s[62:63], 0, v[68:69]
	v_lshlrev_b32_e32 v74, 16, v130
	v_and_b32_e32 v75, 0xffff0000, v130
	v_pk_mul_f32 v[70:71], v[70:71], v[74:75]
	global_load_dwordx4 v[74:77], v[78:79], off offset:256
	v_cvt_pk_bf16_f32 v66, v70, v71
	v_cvt_pk_bf16_f32 v67, v72, v73
	v_lshl_add_u64 v[88:89], v[68:69], 0, v[160:161]
	v_cvt_pk_bf16_f32 v68, v80, v81
	v_cvt_pk_bf16_f32 v69, v86, v87
	global_store_dwordx4 v[162:163], v[66:69], off offset:256
	global_load_dwordx4 v[70:73], v[88:89], off
	s_waitcnt vmcnt(8)
	v_lshlrev_b32_e32 v66, 16, v98
	v_and_b32_e32 v67, 0xffff0000, v98
	v_pk_mul_f32 v[62:63], v[62:63], v[66:67]
	v_lshlrev_b32_e32 v66, 16, v99
	v_and_b32_e32 v67, 0xffff0000, v99
	v_pk_mul_f32 v[66:67], v[64:65], v[66:67]
	v_lshlrev_b32_e32 v64, 16, v100
	v_and_b32_e32 v65, 0xffff0000, v100
	v_pk_mul_f32 v[68:69], v[58:59], v[64:65]
	v_lshlrev_b32_e32 v58, 16, v101
	v_and_b32_e32 v59, 0xffff0000, v101
	v_pk_mul_f32 v[80:81], v[60:61], v[58:59]
	v_cvt_pk_bf16_f32 v58, v62, v63
	v_cvt_pk_bf16_f32 v59, v66, v67
	v_cvt_pk_bf16_f32 v60, v68, v69
	v_cvt_pk_bf16_f32 v61, v80, v81
	global_store_dwordx4 v[94:95], v[58:61], off
	global_load_dwordx4 v[62:65], v[88:89], off offset:256
	s_waitcnt vmcnt(8)
	v_lshlrev_b32_e32 v66, 16, v92
	v_lshlrev_b32_e32 v58, 16, v90
	v_and_b32_e32 v59, 0xffff0000, v90
	v_pk_mul_f32 v[58:59], v[54:55], v[58:59]
	v_lshlrev_b32_e32 v54, 16, v91
	v_and_b32_e32 v55, 0xffff0000, v91
	v_pk_mul_f32 v[60:61], v[56:57], v[54:55]
	v_add_u32_e32 v54, 0xb0, v158
	v_ashrrev_i32_e32 v55, 31, v54
	v_lshlrev_b64 v[54:55], 11, v[54:55]
	v_lshl_add_u64 v[54:55], s[62:63], 0, v[54:55]
	v_and_b32_e32 v67, 0xffff0000, v92
	v_lshl_add_u64 v[68:69], v[54:55], 0, v[160:161]
	v_pk_mul_f32 v[66:67], v[46:47], v[66:67]
	v_lshlrev_b32_e32 v46, 16, v93
	v_and_b32_e32 v47, 0xffff0000, v93
	global_load_dwordx4 v[54:57], v[68:69], off
	v_pk_mul_f32 v[80:81], v[48:49], v[46:47]
	v_cvt_pk_bf16_f32 v46, v58, v59
	v_cvt_pk_bf16_f32 v47, v60, v61
	v_cvt_pk_bf16_f32 v48, v66, v67
	v_cvt_pk_bf16_f32 v49, v80, v81
	global_store_dwordx4 v[94:95], v[46:49], off offset:256
	s_waitcnt vmcnt(8)
	v_lshlrev_b32_e32 v58, 16, v84
	v_and_b32_e32 v59, 0xffff0000, v84
	v_lshlrev_b32_e32 v46, 16, v82
	v_and_b32_e32 v47, 0xffff0000, v82
	v_pk_mul_f32 v[50:51], v[50:51], v[46:47]
	v_lshlrev_b32_e32 v46, 16, v83
	v_and_b32_e32 v47, 0xffff0000, v83
	v_pk_mul_f32 v[52:53], v[52:53], v[46:47]
	global_load_dwordx4 v[46:49], v[68:69], off offset:256
	v_pk_mul_f32 v[58:59], v[42:43], v[58:59]
	v_lshlrev_b32_e32 v42, 16, v85
	v_and_b32_e32 v43, 0xffff0000, v85
	v_pk_mul_f32 v[60:61], v[44:45], v[42:43]
	v_cvt_pk_bf16_f32 v42, v50, v51
	v_cvt_pk_bf16_f32 v43, v52, v53
	v_cvt_pk_bf16_f32 v44, v58, v59
	v_cvt_pk_bf16_f32 v45, v60, v61
	global_store_dwordx4 v[78:79], v[42:45], off
	s_waitcnt vmcnt(8)
	s_nop 0
	v_lshlrev_b32_e32 v42, 16, v74
	v_and_b32_e32 v43, 0xffff0000, v74
	v_pk_mul_f32 v[34:35], v[34:35], v[42:43]
	v_lshlrev_b32_e32 v42, 16, v75
	v_and_b32_e32 v43, 0xffff0000, v75
	v_pk_mul_f32 v[36:37], v[36:37], v[42:43]
	v_lshlrev_b32_e32 v42, 16, v76
	v_and_b32_e32 v43, 0xffff0000, v76
	v_pk_mul_f32 v[42:43], v[26:27], v[42:43]
	v_lshlrev_b32_e32 v26, 16, v77
	v_and_b32_e32 v27, 0xffff0000, v77
	v_pk_mul_f32 v[44:45], v[28:29], v[26:27]
	v_cvt_pk_bf16_f32 v26, v34, v35
	v_cvt_pk_bf16_f32 v27, v36, v37
	v_cvt_pk_bf16_f32 v28, v42, v43
	v_cvt_pk_bf16_f32 v29, v44, v45
	s_waitcnt vmcnt(6)
	v_lshlrev_b32_e32 v34, 16, v72
	v_and_b32_e32 v35, 0xffff0000, v72
	global_store_dwordx4 v[78:79], v[26:29], off offset:256
	v_pk_mul_f32 v[30:31], v[30:31], v[34:35]
	v_lshlrev_b32_e32 v34, 16, v73
	v_lshlrev_b32_e32 v26, 16, v70
	v_and_b32_e32 v27, 0xffff0000, v70
	v_lshlrev_b32_e32 v28, 16, v71
	v_and_b32_e32 v29, 0xffff0000, v71
	v_and_b32_e32 v35, 0xffff0000, v73
	v_pk_mul_f32 v[26:27], v[38:39], v[26:27]
	v_pk_mul_f32 v[28:29], v[40:41], v[28:29]
	v_pk_mul_f32 v[32:33], v[32:33], v[34:35]
	v_cvt_pk_bf16_f32 v26, v26, v27
	v_cvt_pk_bf16_f32 v27, v28, v29
	v_cvt_pk_bf16_f32 v28, v30, v31
	v_cvt_pk_bf16_f32 v29, v32, v33
	global_store_dwordx4 v[88:89], v[26:29], off
	s_waitcnt vmcnt(6)
	s_nop 0
	v_lshlrev_b32_e32 v26, 16, v62
	v_and_b32_e32 v27, 0xffff0000, v62
	v_pk_mul_f32 v[18:19], v[18:19], v[26:27]
	v_lshlrev_b32_e32 v26, 16, v63
	v_and_b32_e32 v27, 0xffff0000, v63
	v_pk_mul_f32 v[20:21], v[20:21], v[26:27]
	v_lshlrev_b32_e32 v26, 16, v64
	v_and_b32_e32 v27, 0xffff0000, v64
	v_pk_mul_f32 v[26:27], v[10:11], v[26:27]
	v_lshlrev_b32_e32 v10, 16, v65
	v_and_b32_e32 v11, 0xffff0000, v65
	v_pk_mul_f32 v[28:29], v[12:13], v[10:11]
	v_cvt_pk_bf16_f32 v10, v18, v19
	v_cvt_pk_bf16_f32 v11, v20, v21
	v_cvt_pk_bf16_f32 v12, v26, v27
	v_cvt_pk_bf16_f32 v13, v28, v29
	s_waitcnt vmcnt(5)
	v_lshlrev_b32_e32 v18, 16, v56
	v_and_b32_e32 v19, 0xffff0000, v56
	global_store_dwordx4 v[88:89], v[10:13], off offset:256
	v_pk_mul_f32 v[14:15], v[14:15], v[18:19]
	v_lshlrev_b32_e32 v18, 16, v57
	v_lshlrev_b32_e32 v10, 16, v54
	v_and_b32_e32 v11, 0xffff0000, v54
	v_lshlrev_b32_e32 v12, 16, v55
	v_and_b32_e32 v13, 0xffff0000, v55
	v_and_b32_e32 v19, 0xffff0000, v57
	v_pk_mul_f32 v[10:11], v[22:23], v[10:11]
	v_pk_mul_f32 v[12:13], v[24:25], v[12:13]
	v_pk_mul_f32 v[16:17], v[16:17], v[18:19]
	v_cvt_pk_bf16_f32 v10, v10, v11
	v_cvt_pk_bf16_f32 v11, v12, v13
	v_cvt_pk_bf16_f32 v12, v14, v15
	v_cvt_pk_bf16_f32 v13, v16, v17
	global_store_dwordx4 v[68:69], v[10:13], off
	s_waitcnt vmcnt(5)
	s_nop 0
	v_lshlrev_b32_e32 v10, 16, v46
	v_and_b32_e32 v11, 0xffff0000, v46
	v_pk_mul_f32 v[6:7], v[6:7], v[10:11]
	v_lshlrev_b32_e32 v10, 16, v47
	v_and_b32_e32 v11, 0xffff0000, v47
	v_pk_mul_f32 v[8:9], v[8:9], v[10:11]
	v_lshlrev_b32_e32 v10, 16, v48
	v_and_b32_e32 v11, 0xffff0000, v48
	v_pk_mul_f32 v[10:11], v[2:3], v[10:11]
	v_lshlrev_b32_e32 v2, 16, v49
	v_and_b32_e32 v3, 0xffff0000, v49
	v_pk_mul_f32 v[12:13], v[4:5], v[2:3]
	v_cvt_pk_bf16_f32 v2, v6, v7
	v_cvt_pk_bf16_f32 v3, v8, v9
	v_cvt_pk_bf16_f32 v4, v10, v11
	v_cvt_pk_bf16_f32 v5, v12, v13
	global_store_dwordx4 v[68:69], v[2:5], off offset:256
	s_cbranch_vccnz .LBB0_2862
	s_andn2_b64 vcc, exec, s[8:9]
	s_cbranch_vccnz .LBB0_2861
	s_barrier
	s_branch .LBB0_2861
.LBB0_2876:
	s_barrier
.LBB0_2877:
	s_andn2_b64 vcc, exec, s[6:7]
	v_readfirstlane_b32 s0, v168
	s_cbranch_vccnz .LBB0_2898
	s_cmpk_lt_u32 s0, 0x100
	s_cselect_b64 s[8:9], -1, 0
	s_waitcnt lgkmcnt(0)
	v_lshlrev_b32_e32 v3, 3, v168
	s_lshr_b32 s1, s0, 2
	v_bfe_u32 v2, v168, 4, 2
	v_and_b32_e32 v59, 0x78, v3
	s_and_b32 s1, s1, 48
	s_lshr_b32 s3, s0, 4
	v_lshlrev_b32_e32 v38, 1, v59
	v_mov_b32_e32 v39, 0
	v_lshlrev_b32_e32 v4, 3, v2
	s_and_b32 s7, s3, 0xffffffc
	v_lshl_or_b32 v61, v2, 2, s1
	v_add_u32_e32 v2, 0x200, v168
	v_lshl_add_u64 v[42:43], s[4:5], 0, v[38:39]
	v_or_b32_e32 v3, s1, v1
	v_lshrrev_b32_e32 v62, 4, v2
	v_or_b32_e32 v2, 0x400, v168
	s_movk_i32 s4, 0x500
	s_and_b32 s3, s3, 0xffffff0
	s_add_i32 s7, s7, 32
	s_movk_i32 s6, 0x110
	v_mul_u32_u24_e32 v60, 0x110, v3
	v_lshrrev_b32_e32 v3, 4, v2
	v_cmp_gt_u32_e64 s[4:5], s4, v2
	v_or_b32_e32 v2, s3, v1
	s_and_b32 s12, s7, 0x1ffffff0
	v_mul_lo_u32 v68, v2, s6
	v_or_b32_e32 v2, s12, v1
	v_mul_lo_u32 v69, v2, s6
	v_and_b32_e32 v2, 15, v168
	v_lshl_add_u64 v[40:41], s[20:21], 0, v[38:39]
	v_lshlrev_b32_e32 v38, 4, v2
	s_movk_i32 s0, 0x300
	v_cndmask_b32_e64 v64, 0, v3, s[4:5]
	v_mul_u32_u24_e32 v67, 0x110, v3
	v_lshl_add_u64 v[2:3], s[28:29], 0, v[38:39]
	s_mov_b64 s[6:7], 0x7e80100
	v_lshrrev_b32_e32 v58, 4, v168
	v_cmp_gt_u32_e64 s[0:1], s0, v168
	v_lshl_add_u64 v[44:45], v[2:3], 0, s[6:7]
	s_mov_b64 s[6:7], 0x2300100
	v_cndmask_b32_e64 v63, 0, v62, s[0:1]
	v_mul_u32_u24_e32 v65, 0x110, v58
	v_mul_u32_u24_e32 v66, 0x110, v62
	v_mul_u32_u24_e32 v70, 0x110, v1
	v_lshl_add_u64 v[46:47], v[2:3], 0, s[6:7]
	v_lshlrev_b32_e32 v38, 1, v4
	s_mov_b32 s13, s2
	s_branch .LBB0_2880

.LBB0_2922:
	v_readlane_b32 s76, v238, 53
	v_readlane_b32 s77, v238, 54
	s_barrier

.LBB0_3032:
	v_lshl_add_u32 v154, s38, 8, v165
	v_lshl_or_b32 v130, s54, 8, v167
	v_ashrrev_i32_e32 v155, 31, v154
	v_lshlrev_b64 v[132:133], 11, v[154:155]
	v_ashrrev_i32_e32 v131, 31, v130
	v_lshl_add_u64 v[134:135], s[64:65], 0, v[132:133]
	v_lshlrev_b64 v[156:157], 1, v[130:131]
	v_lshl_add_u64 v[132:133], s[62:63], 0, v[132:133]
	v_lshl_add_u64 v[130:131], v[134:135], 0, v[156:157]
	v_lshl_add_u64 v[162:163], v[132:133], 0, v[156:157]
	global_load_dwordx4 v[172:175], v[130:131], off
	global_load_dwordx4 v[176:179], v[162:163], off
	global_load_dwordx4 v[180:183], v[130:131], off offset:256
	global_load_dwordx4 v[184:187], v[162:163], off offset:256
	v_or_b32_e32 v130, 16, v154
	v_ashrrev_i32_e32 v131, 31, v130
	v_lshlrev_b64 v[130:131], 11, v[130:131]
	v_lshl_add_u64 v[132:133], s[64:65], 0, v[130:131]
	v_lshl_add_u64 v[130:131], s[62:63], 0, v[130:131]
	v_lshl_add_u64 v[132:133], v[132:133], 0, v[156:157]
	v_lshl_add_u64 v[158:159], v[130:131], 0, v[156:157]
	global_load_dwordx4 v[188:191], v[132:133], off
	global_load_dwordx4 v[192:195], v[158:159], off
	v_or_b32_e32 v130, 32, v154
	v_ashrrev_i32_e32 v131, 31, v130
	v_lshlrev_b64 v[130:131], 11, v[130:131]
	v_lshl_add_u64 v[134:135], s[64:65], 0, v[130:131]
	v_lshl_add_u64 v[130:131], s[62:63], 0, v[130:131]
	v_lshl_add_u64 v[204:205], v[134:135], 0, v[156:157]
	v_lshl_add_u64 v[160:161], v[130:131], 0, v[156:157]
	global_load_dwordx4 v[196:199], v[132:133], off offset:256
	global_load_dwordx4 v[200:203], v[158:159], off offset:256
	global_load_dwordx4 v[134:137], v[204:205], off
	s_nop 0
	global_load_dwordx4 v[130:133], v[160:161], off
	s_andn2_b64 vcc, exec, s[0:1]
	s_mov_b64 s[0:1], -1
	s_waitcnt vmcnt(0)
	v_lshlrev_b32_e32 v212, 16, v178
	v_lshlrev_b32_e32 v210, 16, v174
	v_and_b32_e32 v211, 0xffff0000, v174
	v_and_b32_e32 v213, 0xffff0000, v178
	v_lshlrev_b32_e32 v174, 16, v175
	v_and_b32_e32 v175, 0xffff0000, v175
	v_lshlrev_b32_e32 v178, 16, v179
	v_and_b32_e32 v179, 0xffff0000, v179
	v_lshlrev_b32_e32 v218, 16, v182
	v_and_b32_e32 v219, 0xffff0000, v182
	v_lshlrev_b32_e32 v220, 16, v186
	v_and_b32_e32 v221, 0xffff0000, v186
	v_lshlrev_b32_e32 v182, 16, v183
	v_and_b32_e32 v183, 0xffff0000, v183
	v_lshlrev_b32_e32 v186, 16, v187
	v_and_b32_e32 v187, 0xffff0000, v187
	v_pk_fma_f32 v[122:123], v[122:123], v[210:211], v[212:213]
	v_pk_fma_f32 v[124:125], v[124:125], v[174:175], v[178:179]
	v_lshlrev_b32_e32 v206, 16, v172
	v_and_b32_e32 v207, 0xffff0000, v172
	v_lshlrev_b32_e32 v208, 16, v176
	v_and_b32_e32 v209, 0xffff0000, v176
	v_lshlrev_b32_e32 v172, 16, v173
	v_and_b32_e32 v173, 0xffff0000, v173
	v_lshlrev_b32_e32 v176, 16, v177
	v_and_b32_e32 v177, 0xffff0000, v177
	v_pk_fma_f32 v[174:175], v[116:117], v[182:183], v[186:187]
	v_cvt_pk_bf16_f32 v116, v122, v123
	v_cvt_pk_bf16_f32 v117, v124, v125
	v_lshlrev_b32_e32 v122, 16, v189
	v_and_b32_e32 v123, 0xffff0000, v189
	v_lshlrev_b32_e32 v124, 16, v193
	v_and_b32_e32 v125, 0xffff0000, v193
	v_lshlrev_b32_e32 v214, 16, v180
	v_and_b32_e32 v215, 0xffff0000, v180
	v_lshlrev_b32_e32 v216, 16, v184
	v_and_b32_e32 v217, 0xffff0000, v184
	v_lshlrev_b32_e32 v180, 16, v181
	v_and_b32_e32 v181, 0xffff0000, v181
	v_lshlrev_b32_e32 v184, 16, v185
	v_and_b32_e32 v185, 0xffff0000, v185
	v_pk_fma_f32 v[126:127], v[126:127], v[206:207], v[208:209]
	v_pk_fma_f32 v[128:129], v[128:129], v[172:173], v[176:177]
	v_pk_fma_f32 v[112:113], v[112:113], v[122:123], v[124:125]
	v_lshlrev_b32_e32 v122, 16, v190
	v_and_b32_e32 v123, 0xffff0000, v190
	v_lshlrev_b32_e32 v124, 16, v194
	v_and_b32_e32 v125, 0xffff0000, v194
	v_pk_fma_f32 v[118:119], v[118:119], v[214:215], v[216:217]
	v_pk_fma_f32 v[120:121], v[120:121], v[180:181], v[184:185]
	v_pk_fma_f32 v[172:173], v[114:115], v[218:219], v[220:221]
	v_lshlrev_b32_e32 v176, 16, v188
	v_and_b32_e32 v177, 0xffff0000, v188
	v_lshlrev_b32_e32 v178, 16, v192
	v_and_b32_e32 v179, 0xffff0000, v192
	v_cvt_pk_bf16_f32 v114, v126, v127
	v_cvt_pk_bf16_f32 v115, v128, v129
	v_pk_fma_f32 v[122:123], v[106:107], v[122:123], v[124:125]
	v_lshlrev_b32_e32 v106, 16, v191
	v_and_b32_e32 v107, 0xffff0000, v191
	v_lshlrev_b32_e32 v124, 16, v195
	v_and_b32_e32 v125, 0xffff0000, v195
	v_cvt_pk_bf16_f32 v118, v118, v119
	v_cvt_pk_bf16_f32 v119, v120, v121
	v_cvt_pk_bf16_f32 v120, v172, v173
	v_cvt_pk_bf16_f32 v121, v174, v175
	v_pk_fma_f32 v[110:111], v[110:111], v[176:177], v[178:179]
	global_store_dwordx4 v[162:163], v[114:117], off
	global_store_dwordx4 v[162:163], v[118:121], off offset:256
	v_pk_fma_f32 v[124:125], v[108:109], v[106:107], v[124:125]
	global_load_dwordx4 v[114:117], v[204:205], off offset:256
	global_load_dwordx4 v[118:121], v[160:161], off offset:256
	v_cvt_pk_bf16_f32 v106, v110, v111
	v_cvt_pk_bf16_f32 v107, v112, v113
	v_cvt_pk_bf16_f32 v108, v122, v123
	v_cvt_pk_bf16_f32 v109, v124, v125
	global_store_dwordx4 v[158:159], v[106:109], off
	v_lshlrev_b32_e32 v124, 16, v196
	v_and_b32_e32 v125, 0xffff0000, v196
	v_or_b32_e32 v106, 48, v154
	v_ashrrev_i32_e32 v107, 31, v106
	v_lshlrev_b64 v[110:111], 11, v[106:107]
	v_lshl_add_u64 v[106:107], s[64:65], 0, v[110:111]
	v_lshl_add_u64 v[110:111], s[62:63], 0, v[110:111]
	v_lshl_add_u64 v[122:123], v[106:107], 0, v[156:157]
	v_lshl_add_u64 v[126:127], v[110:111], 0, v[156:157]
	global_load_dwordx4 v[106:109], v[122:123], off
	global_load_dwordx4 v[110:113], v[126:127], off
	v_lshlrev_b32_e32 v128, 16, v200
	v_and_b32_e32 v129, 0xffff0000, v200
	v_pk_fma_f32 v[102:103], v[102:103], v[124:125], v[128:129]
	v_lshlrev_b32_e32 v124, 16, v197
	v_and_b32_e32 v125, 0xffff0000, v197
	v_lshlrev_b32_e32 v128, 16, v201
	v_and_b32_e32 v129, 0xffff0000, v201
	v_pk_fma_f32 v[104:105], v[104:105], v[124:125], v[128:129]
	v_lshlrev_b32_e32 v124, 16, v198
	v_and_b32_e32 v125, 0xffff0000, v198
	v_lshlrev_b32_e32 v128, 16, v202
	v_and_b32_e32 v129, 0xffff0000, v202
	v_pk_fma_f32 v[124:125], v[98:99], v[124:125], v[128:129]
	v_lshlrev_b32_e32 v98, 16, v199
	v_and_b32_e32 v99, 0xffff0000, v199
	v_lshlrev_b32_e32 v128, 16, v203
	v_and_b32_e32 v129, 0xffff0000, v203
	v_pk_fma_f32 v[128:129], v[100:101], v[98:99], v[128:129]
	v_cvt_pk_bf16_f32 v98, v102, v103
	v_cvt_pk_bf16_f32 v99, v104, v105
	global_load_dwordx4 v[102:105], v[122:123], off offset:256
	v_cvt_pk_bf16_f32 v100, v124, v125
	global_load_dwordx4 v[122:125], v[126:127], off offset:256
	v_cvt_pk_bf16_f32 v101, v128, v129
	global_store_dwordx4 v[158:159], v[98:101], off offset:256
	s_nop 1
	v_lshlrev_b32_e32 v98, 16, v134
	v_and_b32_e32 v99, 0xffff0000, v134
	v_lshlrev_b32_e32 v100, 16, v130
	v_and_b32_e32 v101, 0xffff0000, v130
	v_pk_fma_f32 v[94:95], v[94:95], v[98:99], v[100:101]
	v_lshlrev_b32_e32 v98, 16, v135
	v_and_b32_e32 v99, 0xffff0000, v135
	v_lshlrev_b32_e32 v100, 16, v131
	v_and_b32_e32 v101, 0xffff0000, v131
	v_pk_fma_f32 v[96:97], v[96:97], v[98:99], v[100:101]
	v_lshlrev_b32_e32 v98, 16, v136
	v_and_b32_e32 v99, 0xffff0000, v136
	v_lshlrev_b32_e32 v100, 16, v132
	v_and_b32_e32 v101, 0xffff0000, v132
	v_pk_fma_f32 v[98:99], v[90:91], v[98:99], v[100:101]
	v_lshlrev_b32_e32 v90, 16, v137
	v_and_b32_e32 v91, 0xffff0000, v137
	v_lshlrev_b32_e32 v100, 16, v133
	v_and_b32_e32 v101, 0xffff0000, v133
	v_pk_fma_f32 v[100:101], v[92:93], v[90:91], v[100:101]
	v_cvt_pk_bf16_f32 v90, v94, v95
	v_cvt_pk_bf16_f32 v91, v96, v97
	v_cvt_pk_bf16_f32 v92, v98, v99
	v_cvt_pk_bf16_f32 v93, v100, v101
	global_store_dwordx4 v[160:161], v[90:93], off
	s_waitcnt vmcnt(8)
	s_nop 0
	v_lshlrev_b32_e32 v90, 16, v114
	v_and_b32_e32 v91, 0xffff0000, v114
	s_waitcnt vmcnt(7)
	v_lshlrev_b32_e32 v92, 16, v118
	v_and_b32_e32 v93, 0xffff0000, v118
	v_pk_fma_f32 v[86:87], v[86:87], v[90:91], v[92:93]
	v_lshlrev_b32_e32 v90, 16, v115
	v_and_b32_e32 v91, 0xffff0000, v115
	v_lshlrev_b32_e32 v92, 16, v119
	v_and_b32_e32 v93, 0xffff0000, v119
	v_pk_fma_f32 v[88:89], v[88:89], v[90:91], v[92:93]
	v_lshlrev_b32_e32 v90, 16, v116
	v_and_b32_e32 v91, 0xffff0000, v116
	v_lshlrev_b32_e32 v92, 16, v120
	v_and_b32_e32 v93, 0xffff0000, v120
	v_pk_fma_f32 v[90:91], v[78:79], v[90:91], v[92:93]
	v_lshlrev_b32_e32 v78, 16, v117
	v_and_b32_e32 v79, 0xffff0000, v117
	v_lshlrev_b32_e32 v92, 16, v121
	v_and_b32_e32 v93, 0xffff0000, v121
	v_pk_fma_f32 v[92:93], v[80:81], v[78:79], v[92:93]
	v_cvt_pk_bf16_f32 v78, v86, v87
	v_cvt_pk_bf16_f32 v79, v88, v89
	v_cvt_pk_bf16_f32 v80, v90, v91
	v_cvt_pk_bf16_f32 v81, v92, v93
	global_store_dwordx4 v[160:161], v[78:81], off offset:256
	s_waitcnt vmcnt(6)
	s_nop 0
	v_lshlrev_b32_e32 v78, 16, v106
	v_and_b32_e32 v79, 0xffff0000, v106
	s_waitcnt vmcnt(5)
	v_lshlrev_b32_e32 v80, 16, v110
	v_and_b32_e32 v81, 0xffff0000, v110
	v_pk_fma_f32 v[78:79], v[82:83], v[78:79], v[80:81]
	v_lshlrev_b32_e32 v80, 16, v107
	v_and_b32_e32 v81, 0xffff0000, v107
	v_lshlrev_b32_e32 v82, 16, v111
	v_and_b32_e32 v83, 0xffff0000, v111
	v_pk_fma_f32 v[80:81], v[84:85], v[80:81], v[82:83]
	v_lshlrev_b32_e32 v82, 16, v108
	v_and_b32_e32 v83, 0xffff0000, v108
	v_lshlrev_b32_e32 v84, 16, v112
	v_and_b32_e32 v85, 0xffff0000, v112
	v_pk_fma_f32 v[82:83], v[74:75], v[82:83], v[84:85]
	v_lshlrev_b32_e32 v74, 16, v109
	v_and_b32_e32 v75, 0xffff0000, v109
	v_lshlrev_b32_e32 v84, 16, v113
	v_and_b32_e32 v85, 0xffff0000, v113
	v_pk_fma_f32 v[84:85], v[76:77], v[74:75], v[84:85]
	v_cvt_pk_bf16_f32 v74, v78, v79
	v_cvt_pk_bf16_f32 v75, v80, v81
	v_cvt_pk_bf16_f32 v76, v82, v83
	v_cvt_pk_bf16_f32 v77, v84, v85
	global_store_dwordx4 v[126:127], v[74:77], off
	s_waitcnt vmcnt(5)
	v_lshlrev_b32_e32 v82, 16, v102
	v_and_b32_e32 v83, 0xffff0000, v102
	v_add_u32_e32 v74, 0x80, v154
	v_ashrrev_i32_e32 v75, 31, v74
	v_lshlrev_b64 v[78:79], 11, v[74:75]
	v_lshl_add_u64 v[74:75], s[64:65], 0, v[78:79]
	v_lshl_add_u64 v[78:79], s[62:63], 0, v[78:79]
	v_lshl_add_u64 v[86:87], v[74:75], 0, v[156:157]
	v_lshl_add_u64 v[88:89], v[78:79], 0, v[156:157]
	global_load_dwordx4 v[74:77], v[86:87], off
	global_load_dwordx4 v[78:81], v[88:89], off
	s_waitcnt vmcnt(6)
	v_lshlrev_b32_e32 v84, 16, v122
	v_and_b32_e32 v85, 0xffff0000, v122
	v_pk_fma_f32 v[70:71], v[70:71], v[82:83], v[84:85]
	v_lshlrev_b32_e32 v82, 16, v103
	v_and_b32_e32 v83, 0xffff0000, v103
	v_lshlrev_b32_e32 v84, 16, v123
	v_and_b32_e32 v85, 0xffff0000, v123
	v_pk_fma_f32 v[72:73], v[72:73], v[82:83], v[84:85]
	v_lshlrev_b32_e32 v82, 16, v104
	v_and_b32_e32 v83, 0xffff0000, v104
	v_lshlrev_b32_e32 v84, 16, v124
	v_and_b32_e32 v85, 0xffff0000, v124
	v_pk_fma_f32 v[82:83], v[66:67], v[82:83], v[84:85]
	v_lshlrev_b32_e32 v66, 16, v105
	v_and_b32_e32 v67, 0xffff0000, v105
	v_lshlrev_b32_e32 v84, 16, v125
	v_and_b32_e32 v85, 0xffff0000, v125
	v_pk_fma_f32 v[84:85], v[68:69], v[66:67], v[84:85]
	v_cvt_pk_bf16_f32 v66, v70, v71
	v_cvt_pk_bf16_f32 v67, v72, v73
	v_cvt_pk_bf16_f32 v68, v82, v83
	v_cvt_pk_bf16_f32 v69, v84, v85
	global_store_dwordx4 v[126:127], v[66:69], off offset:256
	global_load_dwordx4 v[66:69], v[86:87], off offset:256
	s_nop 0
	global_load_dwordx4 v[70:73], v[88:89], off offset:256
	s_waitcnt vmcnt(4)
	v_lshlrev_b32_e32 v82, 16, v74
	v_and_b32_e32 v83, 0xffff0000, v74
	s_waitcnt vmcnt(3)
	v_lshlrev_b32_e32 v84, 16, v78
	v_and_b32_e32 v85, 0xffff0000, v78
	v_lshlrev_b32_e32 v74, 16, v75
	v_and_b32_e32 v75, 0xffff0000, v75
	v_lshlrev_b32_e32 v78, 16, v79
	v_and_b32_e32 v79, 0xffff0000, v79
	v_pk_fma_f32 v[64:65], v[64:65], v[74:75], v[78:79]
	v_lshlrev_b32_e32 v74, 16, v76
	v_and_b32_e32 v75, 0xffff0000, v76
	v_lshlrev_b32_e32 v78, 16, v80
	v_and_b32_e32 v79, 0xffff0000, v80
	v_pk_fma_f32 v[74:75], v[58:59], v[74:75], v[78:79]
	v_lshlrev_b32_e32 v58, 16, v77
	v_and_b32_e32 v59, 0xffff0000, v77
	v_lshlrev_b32_e32 v76, 16, v81
	v_and_b32_e32 v77, 0xffff0000, v81
	v_pk_fma_f32 v[62:63], v[62:63], v[82:83], v[84:85]
	v_pk_fma_f32 v[76:77], v[60:61], v[58:59], v[76:77]
	v_cvt_pk_bf16_f32 v58, v62, v63
	v_cvt_pk_bf16_f32 v59, v64, v65
	v_cvt_pk_bf16_f32 v60, v74, v75
	v_cvt_pk_bf16_f32 v61, v76, v77
	global_store_dwordx4 v[88:89], v[58:61], off
	s_waitcnt vmcnt(2)
	v_lshlrev_b32_e32 v74, 16, v66
	v_and_b32_e32 v75, 0xffff0000, v66
	v_add_u32_e32 v58, 0x90, v154
	v_ashrrev_i32_e32 v59, 31, v58
	v_lshlrev_b64 v[62:63], 11, v[58:59]
	v_lshl_add_u64 v[58:59], s[64:65], 0, v[62:63]
	v_lshl_add_u64 v[62:63], s[62:63], 0, v[62:63]
	v_lshl_add_u64 v[78:79], v[58:59], 0, v[156:157]
	v_lshl_add_u64 v[80:81], v[62:63], 0, v[156:157]
	global_load_dwordx4 v[58:61], v[78:79], off
	global_load_dwordx4 v[62:65], v[80:81], off
	s_waitcnt vmcnt(3)
	v_lshlrev_b32_e32 v76, 16, v70
	v_and_b32_e32 v77, 0xffff0000, v70
	v_lshlrev_b32_e32 v66, 16, v67
	v_and_b32_e32 v67, 0xffff0000, v67
	v_lshlrev_b32_e32 v70, 16, v71
	v_and_b32_e32 v71, 0xffff0000, v71
	v_pk_fma_f32 v[56:57], v[56:57], v[66:67], v[70:71]
	v_lshlrev_b32_e32 v66, 16, v68
	v_and_b32_e32 v67, 0xffff0000, v68
	v_lshlrev_b32_e32 v70, 16, v72
	v_and_b32_e32 v71, 0xffff0000, v72
	v_pk_fma_f32 v[66:67], v[50:51], v[66:67], v[70:71]
	v_lshlrev_b32_e32 v50, 16, v69
	v_and_b32_e32 v51, 0xffff0000, v69
	v_lshlrev_b32_e32 v68, 16, v73
	v_and_b32_e32 v69, 0xffff0000, v73
	v_pk_fma_f32 v[54:55], v[54:55], v[74:75], v[76:77]
	v_pk_fma_f32 v[68:69], v[52:53], v[50:51], v[68:69]
	v_cvt_pk_bf16_f32 v50, v54, v55
	v_cvt_pk_bf16_f32 v51, v56, v57
	v_cvt_pk_bf16_f32 v52, v66, v67
	v_cvt_pk_bf16_f32 v53, v68, v69
	global_store_dwordx4 v[88:89], v[50:53], off offset:256
	global_load_dwordx4 v[50:53], v[78:79], off offset:256
	s_nop 0
	global_load_dwordx4 v[54:57], v[80:81], off offset:256
	s_waitcnt vmcnt(4)
	v_lshlrev_b32_e32 v66, 16, v58
	v_and_b32_e32 v67, 0xffff0000, v58
	s_waitcnt vmcnt(3)
	v_lshlrev_b32_e32 v68, 16, v62
	v_and_b32_e32 v69, 0xffff0000, v62
	v_lshlrev_b32_e32 v58, 16, v59
	v_and_b32_e32 v59, 0xffff0000, v59
	v_lshlrev_b32_e32 v62, 16, v63
	v_and_b32_e32 v63, 0xffff0000, v63
	v_pk_fma_f32 v[48:49], v[48:49], v[58:59], v[62:63]
	v_lshlrev_b32_e32 v58, 16, v60
	v_and_b32_e32 v59, 0xffff0000, v60
	v_lshlrev_b32_e32 v62, 16, v64
	v_and_b32_e32 v63, 0xffff0000, v64
	v_pk_fma_f32 v[58:59], v[42:43], v[58:59], v[62:63]
	v_lshlrev_b32_e32 v42, 16, v61
	v_and_b32_e32 v43, 0xffff0000, v61
	v_lshlrev_b32_e32 v60, 16, v65
	v_and_b32_e32 v61, 0xffff0000, v65
	v_pk_fma_f32 v[46:47], v[46:47], v[66:67], v[68:69]
	v_pk_fma_f32 v[60:61], v[44:45], v[42:43], v[60:61]
	v_cvt_pk_bf16_f32 v42, v46, v47
	v_cvt_pk_bf16_f32 v43, v48, v49
	v_cvt_pk_bf16_f32 v44, v58, v59
	v_cvt_pk_bf16_f32 v45, v60, v61
	global_store_dwordx4 v[80:81], v[42:45], off
	s_waitcnt vmcnt(2)
	v_lshlrev_b32_e32 v58, 16, v50
	v_and_b32_e32 v59, 0xffff0000, v50
	v_add_u32_e32 v42, 0xa0, v154
	v_ashrrev_i32_e32 v43, 31, v42
	v_lshlrev_b64 v[46:47], 11, v[42:43]
	v_lshl_add_u64 v[42:43], s[64:65], 0, v[46:47]
	v_lshl_add_u64 v[46:47], s[62:63], 0, v[46:47]
	v_lshl_add_u64 v[62:63], v[42:43], 0, v[156:157]
	v_lshl_add_u64 v[64:65], v[46:47], 0, v[156:157]
	global_load_dwordx4 v[42:45], v[62:63], off
	global_load_dwordx4 v[46:49], v[64:65], off
	s_waitcnt vmcnt(3)
	v_lshlrev_b32_e32 v60, 16, v54
	v_and_b32_e32 v61, 0xffff0000, v54
	v_lshlrev_b32_e32 v50, 16, v51
	v_and_b32_e32 v51, 0xffff0000, v51
	v_lshlrev_b32_e32 v54, 16, v55
	v_and_b32_e32 v55, 0xffff0000, v55
	v_pk_fma_f32 v[40:41], v[40:41], v[50:51], v[54:55]
	v_lshlrev_b32_e32 v50, 16, v52
	v_and_b32_e32 v51, 0xffff0000, v52
	v_lshlrev_b32_e32 v54, 16, v56
	v_and_b32_e32 v55, 0xffff0000, v56
	v_pk_fma_f32 v[50:51], v[34:35], v[50:51], v[54:55]
	v_lshlrev_b32_e32 v34, 16, v53
	v_and_b32_e32 v35, 0xffff0000, v53
	v_lshlrev_b32_e32 v52, 16, v57
	v_and_b32_e32 v53, 0xffff0000, v57
	v_pk_fma_f32 v[38:39], v[38:39], v[58:59], v[60:61]
	v_pk_fma_f32 v[52:53], v[36:37], v[34:35], v[52:53]
	v_cvt_pk_bf16_f32 v34, v38, v39
	v_cvt_pk_bf16_f32 v35, v40, v41
	v_cvt_pk_bf16_f32 v36, v50, v51
	v_cvt_pk_bf16_f32 v37, v52, v53
	global_store_dwordx4 v[80:81], v[34:37], off offset:256
	global_load_dwordx4 v[34:37], v[62:63], off offset:256
	s_nop 0
	global_load_dwordx4 v[38:41], v[64:65], off offset:256
	s_waitcnt vmcnt(4)
	v_lshlrev_b32_e32 v50, 16, v42
	v_and_b32_e32 v51, 0xffff0000, v42
	s_waitcnt vmcnt(3)
	v_lshlrev_b32_e32 v52, 16, v46
	v_and_b32_e32 v53, 0xffff0000, v46
	v_lshlrev_b32_e32 v42, 16, v43
	v_and_b32_e32 v43, 0xffff0000, v43
	v_lshlrev_b32_e32 v46, 16, v47
	v_and_b32_e32 v47, 0xffff0000, v47
	v_pk_fma_f32 v[32:33], v[32:33], v[42:43], v[46:47]
	v_lshlrev_b32_e32 v42, 16, v44
	v_and_b32_e32 v43, 0xffff0000, v44
	v_lshlrev_b32_e32 v46, 16, v48
	v_and_b32_e32 v47, 0xffff0000, v48
	v_pk_fma_f32 v[42:43], v[26:27], v[42:43], v[46:47]
	v_lshlrev_b32_e32 v26, 16, v45
	v_and_b32_e32 v27, 0xffff0000, v45
	v_lshlrev_b32_e32 v44, 16, v49
	v_and_b32_e32 v45, 0xffff0000, v49
	v_pk_fma_f32 v[30:31], v[30:31], v[50:51], v[52:53]
	v_pk_fma_f32 v[44:45], v[28:29], v[26:27], v[44:45]
	v_cvt_pk_bf16_f32 v26, v30, v31
	v_cvt_pk_bf16_f32 v27, v32, v33
	v_cvt_pk_bf16_f32 v28, v42, v43
	v_cvt_pk_bf16_f32 v29, v44, v45
	global_store_dwordx4 v[64:65], v[26:29], off
	s_waitcnt vmcnt(2)
	v_lshlrev_b32_e32 v42, 16, v34
	v_and_b32_e32 v43, 0xffff0000, v34
	v_add_u32_e32 v26, 0xb0, v154
	v_ashrrev_i32_e32 v27, 31, v26
	v_lshlrev_b64 v[30:31], 11, v[26:27]
	v_lshl_add_u64 v[26:27], s[64:65], 0, v[30:31]
	v_lshl_add_u64 v[30:31], s[62:63], 0, v[30:31]
	s_waitcnt vmcnt(1)
	v_lshlrev_b32_e32 v44, 16, v38
	v_lshl_add_u64 v[46:47], v[26:27], 0, v[156:157]
	v_lshl_add_u64 v[48:49], v[30:31], 0, v[156:157]
	v_and_b32_e32 v45, 0xffff0000, v38
	v_lshlrev_b32_e32 v34, 16, v35
	v_and_b32_e32 v35, 0xffff0000, v35
	v_lshlrev_b32_e32 v38, 16, v39
	v_and_b32_e32 v39, 0xffff0000, v39
	global_load_dwordx4 v[26:29], v[46:47], off
	global_load_dwordx4 v[30:33], v[48:49], off
	v_pk_fma_f32 v[24:25], v[24:25], v[34:35], v[38:39]
	v_lshlrev_b32_e32 v34, 16, v36
	v_and_b32_e32 v35, 0xffff0000, v36
	v_lshlrev_b32_e32 v38, 16, v40
	v_and_b32_e32 v39, 0xffff0000, v40
	v_pk_fma_f32 v[34:35], v[18:19], v[34:35], v[38:39]
	v_lshlrev_b32_e32 v18, 16, v37
	v_and_b32_e32 v19, 0xffff0000, v37
	v_lshlrev_b32_e32 v36, 16, v41
	v_and_b32_e32 v37, 0xffff0000, v41
	v_pk_fma_f32 v[22:23], v[22:23], v[42:43], v[44:45]
	v_pk_fma_f32 v[36:37], v[20:21], v[18:19], v[36:37]
	v_cvt_pk_bf16_f32 v18, v22, v23
	v_cvt_pk_bf16_f32 v19, v24, v25
	v_cvt_pk_bf16_f32 v20, v34, v35
	v_cvt_pk_bf16_f32 v21, v36, v37
	global_store_dwordx4 v[64:65], v[18:21], off offset:256
	global_load_dwordx4 v[18:21], v[46:47], off offset:256
	s_nop 0
	global_load_dwordx4 v[22:25], v[48:49], off offset:256
	s_waitcnt vmcnt(4)
	v_lshlrev_b32_e32 v34, 16, v26
	v_and_b32_e32 v35, 0xffff0000, v26
	s_waitcnt vmcnt(3)
	v_lshlrev_b32_e32 v36, 16, v30
	v_and_b32_e32 v37, 0xffff0000, v30
	v_lshlrev_b32_e32 v26, 16, v27
	v_and_b32_e32 v27, 0xffff0000, v27
	v_lshlrev_b32_e32 v30, 16, v31
	v_and_b32_e32 v31, 0xffff0000, v31
	v_pk_fma_f32 v[16:17], v[16:17], v[26:27], v[30:31]
	v_lshlrev_b32_e32 v26, 16, v28
	v_and_b32_e32 v27, 0xffff0000, v28
	v_lshlrev_b32_e32 v30, 16, v32
	v_and_b32_e32 v31, 0xffff0000, v32
	v_pk_fma_f32 v[26:27], v[10:11], v[26:27], v[30:31]
	v_lshlrev_b32_e32 v10, 16, v29
	v_and_b32_e32 v11, 0xffff0000, v29
	v_lshlrev_b32_e32 v28, 16, v33
	v_and_b32_e32 v29, 0xffff0000, v33
	v_pk_fma_f32 v[14:15], v[14:15], v[34:35], v[36:37]
	v_pk_fma_f32 v[28:29], v[12:13], v[10:11], v[28:29]
	v_cvt_pk_bf16_f32 v10, v14, v15
	v_cvt_pk_bf16_f32 v11, v16, v17
	v_cvt_pk_bf16_f32 v12, v26, v27
	v_cvt_pk_bf16_f32 v13, v28, v29
	global_store_dwordx4 v[48:49], v[10:13], off
	s_waitcnt vmcnt(2)
	s_nop 0
	v_lshlrev_b32_e32 v10, 16, v18
	v_and_b32_e32 v11, 0xffff0000, v18
	s_waitcnt vmcnt(1)
	v_lshlrev_b32_e32 v12, 16, v22
	v_and_b32_e32 v13, 0xffff0000, v22
	v_pk_fma_f32 v[6:7], v[6:7], v[10:11], v[12:13]
	v_lshlrev_b32_e32 v10, 16, v19
	v_and_b32_e32 v11, 0xffff0000, v19
	v_lshlrev_b32_e32 v12, 16, v23
	v_and_b32_e32 v13, 0xffff0000, v23
	v_pk_fma_f32 v[8:9], v[8:9], v[10:11], v[12:13]
	v_lshlrev_b32_e32 v10, 16, v20
	v_and_b32_e32 v11, 0xffff0000, v20
	v_lshlrev_b32_e32 v12, 16, v24
	v_and_b32_e32 v13, 0xffff0000, v24
	v_pk_fma_f32 v[10:11], v[2:3], v[10:11], v[12:13]
	v_lshlrev_b32_e32 v2, 16, v21
	v_and_b32_e32 v3, 0xffff0000, v21
	v_lshlrev_b32_e32 v12, 16, v25
	v_and_b32_e32 v13, 0xffff0000, v25
	v_pk_fma_f32 v[12:13], v[4:5], v[2:3], v[12:13]
	v_cvt_pk_bf16_f32 v2, v6, v7
	v_cvt_pk_bf16_f32 v3, v8, v9
	v_cvt_pk_bf16_f32 v4, v10, v11
	v_cvt_pk_bf16_f32 v5, v12, v13
	global_store_dwordx4 v[48:49], v[2:5], off offset:256
	s_cbranch_vccnz .LBB0_3021
	s_andn2_b64 vcc, exec, s[10:11]
	s_cbranch_vccnz .LBB0_3020
	s_barrier
	s_branch .LBB0_3020
.LBB0_3035:
	s_barrier
.LBB0_3036:
	s_andn2_b64 vcc, exec, s[6:7]
	v_readfirstlane_b32 s0, v164
	s_cbranch_vccnz .LBB0_3057
	s_cmpk_lt_u32 s0, 0x100
	s_cselect_b64 s[10:11], -1, 0
	s_waitcnt lgkmcnt(0)
	v_lshlrev_b32_e32 v3, 3, v164
	s_lshr_b32 s1, s0, 2
	v_bfe_u32 v2, v164, 4, 2
	v_and_b32_e32 v59, 0x78, v3
	s_and_b32 s1, s1, 48
	s_lshr_b32 s3, s0, 4
	v_lshlrev_b32_e32 v38, 1, v59
	v_mov_b32_e32 v39, 0
	v_lshlrev_b32_e32 v4, 3, v2
	s_and_b32 s7, s3, 0xffffffc
	v_lshl_or_b32 v61, v2, 2, s1
	v_add_u32_e32 v2, 0x200, v164
	v_lshl_add_u64 v[42:43], s[4:5], 0, v[38:39]
	v_or_b32_e32 v3, s1, v1
	v_lshrrev_b32_e32 v62, 4, v2
	v_or_b32_e32 v2, 0x400, v164
	s_movk_i32 s4, 0x500
	s_and_b32 s3, s3, 0xffffff0
	s_add_i32 s7, s7, 32
	v_lshl_add_u64 v[40:41], s[14:15], 0, v[38:39]
	s_movk_i32 s6, 0x110
	v_mul_u32_u24_e32 v60, 0x110, v3
	v_lshrrev_b32_e32 v3, 4, v2
	v_cmp_gt_u32_e64 s[4:5], s4, v2
	v_or_b32_e32 v2, s3, v1
	s_and_b32 s14, s7, 0x1ffffff0
	v_mul_lo_u32 v68, v2, s6
	v_or_b32_e32 v2, s14, v1
	v_mul_lo_u32 v69, v2, s6
	v_and_b32_e32 v2, 15, v164
	v_lshlrev_b32_e32 v38, 4, v2
	s_movk_i32 s0, 0x300
	v_cndmask_b32_e64 v64, 0, v3, s[4:5]
	v_mul_u32_u24_e32 v67, 0x110, v3
	v_lshl_add_u64 v[2:3], s[28:29], 0, v[38:39]
	s_mov_b64 s[6:7], 0xa100100
	v_lshrrev_b32_e32 v58, 4, v164
	v_cmp_gt_u32_e64 s[0:1], s0, v164
	v_lshl_add_u64 v[44:45], v[2:3], 0, s[6:7]
	s_mov_b64 s[6:7], 0x2500100
	v_cndmask_b32_e64 v63, 0, v62, s[0:1]
	v_mul_u32_u24_e32 v65, 0x110, v58
	v_mul_u32_u24_e32 v66, 0x110, v62
	v_mul_u32_u24_e32 v70, 0x110, v1
	v_lshl_add_u64 v[46:47], v[2:3], 0, s[6:7]
	v_lshlrev_b32_e32 v38, 1, v4
	s_mov_b32 s15, s2
	s_branch .LBB0_3039

.LBB0_3182:
	s_or_b64 exec, exec, s[44:45]
	s_andn2_b64 vcc, exec, s[6:7]
	s_mov_b64 s[6:7], -1
	s_cbranch_vccnz .LBB0_3123
	s_andn2_b64 vcc, exec, s[16:17]
	s_cbranch_vccnz .LBB0_3122
	s_barrier
	s_branch .LBB0_3122
.LBB0_3185:
	s_barrier
.LBB0_3186:
	s_and_b64 vcc, exec, s[0:1]
	v_readfirstlane_b32 s0, v1
	s_cbranch_vccnz .LBB0_3221
	s_cmpk_lt_u32 s0, 0x100
	s_cselect_b64 s[16:17], -1, 0
	v_lshlrev_b32_e32 v2, 3, v1
	s_lshr_b32 s3, s0, 2
	v_and_b32_e32 v59, 0x78, v2
	v_and_or_b32 v2, s3, 48, v164
	s_lshr_b32 s1, s0, 6
	v_mul_u32_u24_e32 v60, 0x110, v2
	s_bfe_u32 s4, s0, 0x20006
	v_lshlrev_b32_e32 v2, 2, v165
	v_lshlrev_b32_e32 v38, 1, v59
	v_mov_b32_e32 v39, 0
	s_lshl_b32 s10, s1, 2
	v_lshl_or_b32 v61, s4, 4, v2
	v_add_u32_e32 v2, 0x200, v1
	v_lshl_add_u64 v[42:43], s[8:9], 0, v[38:39]
	v_lshrrev_b32_e32 v62, 4, v2
	v_or_b32_e32 v2, 0x400, v1
	s_movk_i32 s8, 0x500
	s_and_b32 s11, s10, 0xffffff0
	s_add_i32 s10, s10, 32
	s_waitcnt lgkmcnt(0)
	v_lshl_add_u64 v[40:41], s[62:63], 0, v[38:39]
	s_lshl_b32 s4, s4, 2
	v_lshrrev_b32_e32 v3, 4, v2
	v_cmp_gt_u32_e64 s[8:9], s8, v2
	s_and_b32 s10, s10, 0x1ffffff0
	v_lshlrev_b32_e32 v38, 4, v164
	s_add_i32 s4, s4, 0
	v_cndmask_b32_e64 v64, 0, v3, s[8:9]
	v_mul_u32_u24_e32 v67, 0x110, v3
	v_or_b32_e32 v68, s11, v164
	v_or_b32_e32 v70, s10, v164
	v_lshl_add_u64 v[2:3], s[28:29], 0, v[38:39]
	s_mov_b64 s[10:11], 0xc380100
	s_movk_i32 s3, 0x110
	s_add_i32 s18, s4, 0x13200
	s_movk_i32 s6, 0x300
	v_lshl_add_u64 v[44:45], v[2:3], 0, s[10:11]
	s_mov_b64 s[10:11], 0x2700100
	v_lshrrev_b32_e32 v58, 4, v1
	s_movk_i32 s4, 0x50
	v_cmp_gt_u32_e64 s[6:7], s6, v1
	v_mul_lo_u32 v69, v68, s3
	v_mul_lo_u32 v71, v70, s3
	v_lshlrev_b32_e32 v4, 4, v68
	v_lshlrev_b32_e32 v5, 4, v70
	s_add_u32 s3, s28, 0xea61400
	v_lshl_add_u64 v[46:47], v[2:3], 0, s[10:11]
	v_mbcnt_lo_u32_b32 v2, -1, 0
	v_cmp_eq_u32_e64 s[0:1], 0, v165
	v_cmp_gt_u32_e64 s[4:5], s4, v1
	v_cndmask_b32_e64 v63, 0, v62, s[6:7]
	v_mul_u32_u24_e32 v65, 0x110, v58
	v_mul_u32_u24_e32 v66, 0x110, v62
	v_mul_u32_u24_e32 v72, 0x110, v164
	v_or_b32_e32 v73, 0x4040, v164
	s_addc_u32 s22, s29, 0
	s_movk_i32 s23, 0x4400
	v_add_u32_e32 v74, s18, v4
	v_add_u32_e32 v75, s18, v5
	v_add_u32_e32 v38, s18, v38
	v_mbcnt_hi_u32_b32 v76, -1, v2
	s_mov_b32 s33, s2
	s_branch .LBB0_3189
